# p0_rms_pipelined
# speedup vs baseline: 1.0096x; 1.0096x over previous
.LBB0_15:
	v_mov_b32_e32 v0, v181
	s_cmpk_gt_i32 s2, 0x255f
	v_mbcnt_lo_u32_b32 v183, -1, 0
	s_cbranch_scc1 .LBB0_44
	v_lshlrev_b32_e32 v1, 2, v0
	v_and_b32_e32 v12, 0xfc, v1
	v_max_i32_e32 v1, 0xf00, v0
	v_mov_b32_e32 v3, 0
	v_lshlrev_b32_e32 v2, 1, v12
	v_sub_u32_e32 v1, v1, v0
	v_lshl_add_u64 v[4:5], s[50:51], 0, v[2:3]
	v_lshlrev_b32_e32 v2, 2, v12
	v_add_u32_e32 v1, 0xff, v1
	s_waitcnt lgkmcnt(0)
	v_lshl_add_u64 v[10:11], s[62:63], 0, v[2:3]
	v_lshrrev_b32_e32 v2, 8, v1
	v_add_u32_e32 v13, 1, v2
	v_add_u32_e32 v2, -1, v2
	v_lshrrev_b32_e32 v14, 1, v2
	v_and_b32_e32 v6, 63, v0
	v_add_u32_e32 v14, 1, v14
	v_and_b32_e32 v15, 0x1fffffe, v13
	v_mbcnt_hi_u32_b32 v22, -1, v183
	s_movk_i32 s0, 0x1000
	v_lshlrev_b32_e32 v8, 2, v6
	s_movk_i32 s4, 0xff
	v_and_b32_e32 v19, 3, v14
	v_cmp_ne_u32_e64 s[10:11], v13, v15
	v_and_b32_e32 v13, 64, v22
	v_ashrrev_i32_e32 v7, 6, v0
	v_cmp_gt_i32_e64 s[0:1], s0, v0
	v_lshl_or_b32 v9, v6, 8, v8
	v_cmp_lt_u32_e64 s[4:5], s4, v1
	v_lshl_add_u32 v18, v15, 8, v0
	v_add_u32_e32 v1, 0x100, v0
	v_cmp_lt_u32_e64 s[6:7], 5, v2
	v_and_b32_e32 v20, -4, v14
	v_cmp_ne_u32_e64 s[8:9], 0, v19
	s_movk_i32 s62, 0xdfc0
	s_movk_i32 s63, 0x1010
	s_movk_i32 s68, 0x4040
	s_movk_i32 s69, 0x104
	s_movk_i32 s70, 0xeff
	s_mov_b32 s71, 0x10200000
	s_mov_b32 s72, 0x8000
	v_lshlrev_b32_e32 v12, 2, v12
	v_mov_b32_e32 v21, 0x358637bd
	s_mov_b32 s73, 0x800000
	v_lshlrev_b32_e32 v2, 1, v6
	v_add_u32_e32 v23, 64, v13
	v_xor_b32_e32 v24, 32, v22
	v_xor_b32_e32 v25, 16, v22
	v_xor_b32_e32 v26, 8, v22
	v_xor_b32_e32 v27, 4, v22
	v_xor_b32_e32 v28, 2, v22
	v_xor_b32_e32 v29, 1, v22
	s_mov_b32 s74, s2
	s_cmpk_lt_i32 s74, 0x2040
	s_cbranch_scc0 .Lrms_done
	v_and_b32_e32 v64, 63, v181
	v_lshrrev_b32_e32 v65, 6, v181
	v_lshlrev_b32_e32 v66, 4, v64
	v_lshlrev_b32_e32 v67, 3, v64
	global_load_dwordx4 v[68:71], v[10:11], off
	global_load_dwordx4 v[72:75], v[10:11], off offset:1024
	global_load_dwordx4 v[76:79], v[10:11], off offset:2048
	global_load_dwordx4 v[80:83], v[10:11], off offset:3072
	s_cmpk_lt_u32 s74, 0x2000
	s_cselect_b32 s84, s52, s54
	s_cselect_b32 s85, s53, s55
	s_cselect_b32 s86, 0, 0x2000
	s_sub_u32 s86, s74, s86
	v_lshl_add_u32 v84, s86, 2, v65
	v_lshl_add_u32 v84, v84, 12, v66
	v_lshl_add_u32 v86, s74, 2, v65
	v_lshl_add_u32 v86, v86, 11, v67
	global_load_dwordx4 v[88:91], v84, s[84:85] nt
	global_load_dwordx4 v[92:95], v84, s[84:85] offset:1024 nt
	global_load_dwordx4 v[96:99], v84, s[84:85] offset:2048 nt
	global_load_dwordx4 v[100:103], v84, s[84:85] offset:3072 nt
	s_add_i32 s80, s74, s22
	s_cmpk_lt_i32 s80, 0x2040
	s_cbranch_scc0 .Lrms_last0
	s_cmpk_lt_u32 s80, 0x2000
	s_cselect_b32 s84, s52, s54
	s_cselect_b32 s85, s53, s55
	s_cselect_b32 s86, 0, 0x2000
	s_sub_u32 s86, s80, s86
	v_lshl_add_u32 v85, s86, 2, v65
	v_lshl_add_u32 v85, v85, 12, v66
	v_lshl_add_u32 v87, s80, 2, v65
	v_lshl_add_u32 v87, v87, 11, v67
	global_load_dwordx4 v[104:107], v85, s[84:85] nt
	global_load_dwordx4 v[108:111], v85, s[84:85] offset:1024 nt
	global_load_dwordx4 v[112:115], v85, s[84:85] offset:2048 nt
	global_load_dwordx4 v[116:119], v85, s[84:85] offset:3072 nt
	s_waitcnt vmcnt(4)
	v_mul_f32_e32 v120, v88, v88
	v_fmac_f32_e32 v120, v89, v89
	v_fmac_f32_e32 v120, v90, v90
	v_fmac_f32_e32 v120, v91, v91
	v_fmac_f32_e32 v120, v92, v92
	v_fmac_f32_e32 v120, v93, v93
	v_fmac_f32_e32 v120, v94, v94
	v_fmac_f32_e32 v120, v95, v95
	v_fmac_f32_e32 v120, v96, v96
	v_fmac_f32_e32 v120, v97, v97
	v_fmac_f32_e32 v120, v98, v98
	v_fmac_f32_e32 v120, v99, v99
	v_fmac_f32_e32 v120, v100, v100
	v_fmac_f32_e32 v120, v101, v101
	v_fmac_f32_e32 v120, v102, v102
	v_fmac_f32_e32 v120, v103, v103
	s_nop 1
	v_add_f32_dpp v120, v120, v120 quad_perm:[1,0,3,2] row_mask:0xf bank_mask:0xf
	s_nop 1
	v_add_f32_dpp v120, v120, v120 quad_perm:[2,3,0,1] row_mask:0xf bank_mask:0xf
	s_nop 1
	v_add_f32_dpp v120, v120, v120 row_half_mirror row_mask:0xf bank_mask:0xf
	s_nop 1
	v_add_f32_dpp v120, v120, v120 row_mirror row_mask:0xf bank_mask:0xf
	s_nop 1
	v_readlane_b32 s87, v120, 0
	v_readlane_b32 s88, v120, 16
	v_readlane_b32 s89, v120, 32
	v_readlane_b32 s90, v120, 48
	s_nop 1
	v_mov_b32_e32 v121, s87
	v_add_f32_e32 v121, s88, v121
	v_add_f32_e32 v121, s89, v121
	v_add_f32_e32 v121, s90, v121
	v_mov_b32_e32 v122, 0x358637bd
	v_fmamk_f32 v121, v121, 0x3a800000, v122
	v_rsq_f32_e32 v121, v121
	s_nop 0
	v_mul_f32_e32 v88, v88, v121
	v_mul_f32_e32 v89, v89, v121
	v_mul_f32_e32 v90, v90, v121
	v_mul_f32_e32 v91, v91, v121
	v_mul_f32_e32 v92, v92, v121
	v_mul_f32_e32 v93, v93, v121
	v_mul_f32_e32 v94, v94, v121
	v_mul_f32_e32 v95, v95, v121
	v_mul_f32_e32 v96, v96, v121
	v_mul_f32_e32 v97, v97, v121
	v_mul_f32_e32 v98, v98, v121
	v_mul_f32_e32 v99, v99, v121
	v_mul_f32_e32 v100, v100, v121
	v_mul_f32_e32 v101, v101, v121
	v_mul_f32_e32 v102, v102, v121
	v_mul_f32_e32 v103, v103, v121
	v_mul_f32_e32 v88, v68, v88
	v_mul_f32_e32 v89, v69, v89
	v_mul_f32_e32 v90, v70, v90
	v_mul_f32_e32 v91, v71, v91
	v_mul_f32_e32 v92, v72, v92
	v_mul_f32_e32 v93, v73, v93
	v_mul_f32_e32 v94, v74, v94
	v_mul_f32_e32 v95, v75, v95
	v_mul_f32_e32 v96, v76, v96
	v_mul_f32_e32 v97, v77, v97
	v_mul_f32_e32 v98, v78, v98
	v_mul_f32_e32 v99, v79, v99
	v_mul_f32_e32 v100, v80, v100
	v_mul_f32_e32 v101, v81, v101
	v_mul_f32_e32 v102, v82, v102
	v_mul_f32_e32 v103, v83, v103
	v_cvt_pk_bf16_f32 v124, v88, v89
	v_cvt_pk_bf16_f32 v125, v90, v91
	v_cvt_pk_bf16_f32 v126, v92, v93
	v_cvt_pk_bf16_f32 v127, v94, v95
	v_cvt_pk_bf16_f32 v128, v96, v97
	v_cvt_pk_bf16_f32 v129, v98, v99
	v_cvt_pk_bf16_f32 v130, v100, v101
	v_cvt_pk_bf16_f32 v131, v102, v103
	global_store_dwordx2 v86, v[124:125], s[50:51]
	global_store_dwordx2 v86, v[126:127], s[50:51] offset:512
	global_store_dwordx2 v86, v[128:129], s[50:51] offset:1024
	global_store_dwordx2 v86, v[130:131], s[50:51] offset:1536
	s_mov_b32 s74, s80
.Lrms_loop:
	s_add_i32 s80, s74, s22
	s_cmpk_lt_i32 s80, 0x2040
	s_cbranch_scc0 .Lrms_last1
	s_cmpk_lt_u32 s80, 0x2000
	s_cselect_b32 s84, s52, s54
	s_cselect_b32 s85, s53, s55
	s_cselect_b32 s86, 0, 0x2000
	s_sub_u32 s86, s80, s86
	v_lshl_add_u32 v84, s86, 2, v65
	v_lshl_add_u32 v84, v84, 12, v66
	v_lshl_add_u32 v86, s80, 2, v65
	v_lshl_add_u32 v86, v86, 11, v67
	global_load_dwordx4 v[88:91], v84, s[84:85] nt
	global_load_dwordx4 v[92:95], v84, s[84:85] offset:1024 nt
	global_load_dwordx4 v[96:99], v84, s[84:85] offset:2048 nt
	global_load_dwordx4 v[100:103], v84, s[84:85] offset:3072 nt
	s_waitcnt vmcnt(8)
	v_mul_f32_e32 v120, v104, v104
	v_fmac_f32_e32 v120, v105, v105
	v_fmac_f32_e32 v120, v106, v106
	v_fmac_f32_e32 v120, v107, v107
	v_fmac_f32_e32 v120, v108, v108
	v_fmac_f32_e32 v120, v109, v109
	v_fmac_f32_e32 v120, v110, v110
	v_fmac_f32_e32 v120, v111, v111
	v_fmac_f32_e32 v120, v112, v112
	v_fmac_f32_e32 v120, v113, v113
	v_fmac_f32_e32 v120, v114, v114
	v_fmac_f32_e32 v120, v115, v115
	v_fmac_f32_e32 v120, v116, v116
	v_fmac_f32_e32 v120, v117, v117
	v_fmac_f32_e32 v120, v118, v118
	v_fmac_f32_e32 v120, v119, v119
	s_nop 1
	v_add_f32_dpp v120, v120, v120 quad_perm:[1,0,3,2] row_mask:0xf bank_mask:0xf
	s_nop 1
	v_add_f32_dpp v120, v120, v120 quad_perm:[2,3,0,1] row_mask:0xf bank_mask:0xf
	s_nop 1
	v_add_f32_dpp v120, v120, v120 row_half_mirror row_mask:0xf bank_mask:0xf
	s_nop 1
	v_add_f32_dpp v120, v120, v120 row_mirror row_mask:0xf bank_mask:0xf
	s_nop 1
	v_readlane_b32 s87, v120, 0
	v_readlane_b32 s88, v120, 16
	v_readlane_b32 s89, v120, 32
	v_readlane_b32 s90, v120, 48
	s_nop 1
	v_mov_b32_e32 v121, s87
	v_add_f32_e32 v121, s88, v121
	v_add_f32_e32 v121, s89, v121
	v_add_f32_e32 v121, s90, v121
	v_mov_b32_e32 v122, 0x358637bd
	v_fmamk_f32 v121, v121, 0x3a800000, v122
	v_rsq_f32_e32 v121, v121
	s_nop 0
	v_mul_f32_e32 v104, v104, v121
	v_mul_f32_e32 v105, v105, v121
	v_mul_f32_e32 v106, v106, v121
	v_mul_f32_e32 v107, v107, v121
	v_mul_f32_e32 v108, v108, v121
	v_mul_f32_e32 v109, v109, v121
	v_mul_f32_e32 v110, v110, v121
	v_mul_f32_e32 v111, v111, v121
	v_mul_f32_e32 v112, v112, v121
	v_mul_f32_e32 v113, v113, v121
	v_mul_f32_e32 v114, v114, v121
	v_mul_f32_e32 v115, v115, v121
	v_mul_f32_e32 v116, v116, v121
	v_mul_f32_e32 v117, v117, v121
	v_mul_f32_e32 v118, v118, v121
	v_mul_f32_e32 v119, v119, v121
	v_mul_f32_e32 v104, v68, v104
	v_mul_f32_e32 v105, v69, v105
	v_mul_f32_e32 v106, v70, v106
	v_mul_f32_e32 v107, v71, v107
	v_mul_f32_e32 v108, v72, v108
	v_mul_f32_e32 v109, v73, v109
	v_mul_f32_e32 v110, v74, v110
	v_mul_f32_e32 v111, v75, v111
	v_mul_f32_e32 v112, v76, v112
	v_mul_f32_e32 v113, v77, v113
	v_mul_f32_e32 v114, v78, v114
	v_mul_f32_e32 v115, v79, v115
	v_mul_f32_e32 v116, v80, v116
	v_mul_f32_e32 v117, v81, v117
	v_mul_f32_e32 v118, v82, v118
	v_mul_f32_e32 v119, v83, v119
	v_cvt_pk_bf16_f32 v124, v104, v105
	v_cvt_pk_bf16_f32 v125, v106, v107
	v_cvt_pk_bf16_f32 v126, v108, v109
	v_cvt_pk_bf16_f32 v127, v110, v111
	v_cvt_pk_bf16_f32 v128, v112, v113
	v_cvt_pk_bf16_f32 v129, v114, v115
	v_cvt_pk_bf16_f32 v130, v116, v117
	v_cvt_pk_bf16_f32 v131, v118, v119
	global_store_dwordx2 v87, v[124:125], s[50:51]
	global_store_dwordx2 v87, v[126:127], s[50:51] offset:512
	global_store_dwordx2 v87, v[128:129], s[50:51] offset:1024
	global_store_dwordx2 v87, v[130:131], s[50:51] offset:1536
	s_mov_b32 s74, s80
	s_add_i32 s80, s74, s22
	s_cmpk_lt_i32 s80, 0x2040
	s_cbranch_scc0 .Lrms_last0
	s_cmpk_lt_u32 s80, 0x2000
	s_cselect_b32 s84, s52, s54
	s_cselect_b32 s85, s53, s55
	s_cselect_b32 s86, 0, 0x2000
	s_sub_u32 s86, s80, s86
	v_lshl_add_u32 v85, s86, 2, v65
	v_lshl_add_u32 v85, v85, 12, v66
	v_lshl_add_u32 v87, s80, 2, v65
	v_lshl_add_u32 v87, v87, 11, v67
	global_load_dwordx4 v[104:107], v85, s[84:85] nt
	global_load_dwordx4 v[108:111], v85, s[84:85] offset:1024 nt
	global_load_dwordx4 v[112:115], v85, s[84:85] offset:2048 nt
	global_load_dwordx4 v[116:119], v85, s[84:85] offset:3072 nt
	s_waitcnt vmcnt(8)
	v_mul_f32_e32 v120, v88, v88
	v_fmac_f32_e32 v120, v89, v89
	v_fmac_f32_e32 v120, v90, v90
	v_fmac_f32_e32 v120, v91, v91
	v_fmac_f32_e32 v120, v92, v92
	v_fmac_f32_e32 v120, v93, v93
	v_fmac_f32_e32 v120, v94, v94
	v_fmac_f32_e32 v120, v95, v95
	v_fmac_f32_e32 v120, v96, v96
	v_fmac_f32_e32 v120, v97, v97
	v_fmac_f32_e32 v120, v98, v98
	v_fmac_f32_e32 v120, v99, v99
	v_fmac_f32_e32 v120, v100, v100
	v_fmac_f32_e32 v120, v101, v101
	v_fmac_f32_e32 v120, v102, v102
	v_fmac_f32_e32 v120, v103, v103
	s_nop 1
	v_add_f32_dpp v120, v120, v120 quad_perm:[1,0,3,2] row_mask:0xf bank_mask:0xf
	s_nop 1
	v_add_f32_dpp v120, v120, v120 quad_perm:[2,3,0,1] row_mask:0xf bank_mask:0xf
	s_nop 1
	v_add_f32_dpp v120, v120, v120 row_half_mirror row_mask:0xf bank_mask:0xf
	s_nop 1
	v_add_f32_dpp v120, v120, v120 row_mirror row_mask:0xf bank_mask:0xf
	s_nop 1
	v_readlane_b32 s87, v120, 0
	v_readlane_b32 s88, v120, 16
	v_readlane_b32 s89, v120, 32
	v_readlane_b32 s90, v120, 48
	s_nop 1
	v_mov_b32_e32 v121, s87
	v_add_f32_e32 v121, s88, v121
	v_add_f32_e32 v121, s89, v121
	v_add_f32_e32 v121, s90, v121
	v_mov_b32_e32 v122, 0x358637bd
	v_fmamk_f32 v121, v121, 0x3a800000, v122
	v_rsq_f32_e32 v121, v121
	s_nop 0
	v_mul_f32_e32 v88, v88, v121
	v_mul_f32_e32 v89, v89, v121
	v_mul_f32_e32 v90, v90, v121
	v_mul_f32_e32 v91, v91, v121
	v_mul_f32_e32 v92, v92, v121
	v_mul_f32_e32 v93, v93, v121
	v_mul_f32_e32 v94, v94, v121
	v_mul_f32_e32 v95, v95, v121
	v_mul_f32_e32 v96, v96, v121
	v_mul_f32_e32 v97, v97, v121
	v_mul_f32_e32 v98, v98, v121
	v_mul_f32_e32 v99, v99, v121
	v_mul_f32_e32 v100, v100, v121
	v_mul_f32_e32 v101, v101, v121
	v_mul_f32_e32 v102, v102, v121
	v_mul_f32_e32 v103, v103, v121
	v_mul_f32_e32 v88, v68, v88
	v_mul_f32_e32 v89, v69, v89
	v_mul_f32_e32 v90, v70, v90
	v_mul_f32_e32 v91, v71, v91
	v_mul_f32_e32 v92, v72, v92
	v_mul_f32_e32 v93, v73, v93
	v_mul_f32_e32 v94, v74, v94
	v_mul_f32_e32 v95, v75, v95
	v_mul_f32_e32 v96, v76, v96
	v_mul_f32_e32 v97, v77, v97
	v_mul_f32_e32 v98, v78, v98
	v_mul_f32_e32 v99, v79, v99
	v_mul_f32_e32 v100, v80, v100
	v_mul_f32_e32 v101, v81, v101
	v_mul_f32_e32 v102, v82, v102
	v_mul_f32_e32 v103, v83, v103
	v_cvt_pk_bf16_f32 v124, v88, v89
	v_cvt_pk_bf16_f32 v125, v90, v91
	v_cvt_pk_bf16_f32 v126, v92, v93
	v_cvt_pk_bf16_f32 v127, v94, v95
	v_cvt_pk_bf16_f32 v128, v96, v97
	v_cvt_pk_bf16_f32 v129, v98, v99
	v_cvt_pk_bf16_f32 v130, v100, v101
	v_cvt_pk_bf16_f32 v131, v102, v103
	global_store_dwordx2 v86, v[124:125], s[50:51]
	global_store_dwordx2 v86, v[126:127], s[50:51] offset:512
	global_store_dwordx2 v86, v[128:129], s[50:51] offset:1024
	global_store_dwordx2 v86, v[130:131], s[50:51] offset:1536
	s_mov_b32 s74, s80
	s_branch .Lrms_loop
.Lrms_last0:
	s_waitcnt vmcnt(0)
	v_mul_f32_e32 v120, v88, v88
	v_fmac_f32_e32 v120, v89, v89
	v_fmac_f32_e32 v120, v90, v90
	v_fmac_f32_e32 v120, v91, v91
	v_fmac_f32_e32 v120, v92, v92
	v_fmac_f32_e32 v120, v93, v93
	v_fmac_f32_e32 v120, v94, v94
	v_fmac_f32_e32 v120, v95, v95
	v_fmac_f32_e32 v120, v96, v96
	v_fmac_f32_e32 v120, v97, v97
	v_fmac_f32_e32 v120, v98, v98
	v_fmac_f32_e32 v120, v99, v99
	v_fmac_f32_e32 v120, v100, v100
	v_fmac_f32_e32 v120, v101, v101
	v_fmac_f32_e32 v120, v102, v102
	v_fmac_f32_e32 v120, v103, v103
	s_nop 1
	v_add_f32_dpp v120, v120, v120 quad_perm:[1,0,3,2] row_mask:0xf bank_mask:0xf
	s_nop 1
	v_add_f32_dpp v120, v120, v120 quad_perm:[2,3,0,1] row_mask:0xf bank_mask:0xf
	s_nop 1
	v_add_f32_dpp v120, v120, v120 row_half_mirror row_mask:0xf bank_mask:0xf
	s_nop 1
	v_add_f32_dpp v120, v120, v120 row_mirror row_mask:0xf bank_mask:0xf
	s_nop 1
	v_readlane_b32 s87, v120, 0
	v_readlane_b32 s88, v120, 16
	v_readlane_b32 s89, v120, 32
	v_readlane_b32 s90, v120, 48
	s_nop 1
	v_mov_b32_e32 v121, s87
	v_add_f32_e32 v121, s88, v121
	v_add_f32_e32 v121, s89, v121
	v_add_f32_e32 v121, s90, v121
	v_mov_b32_e32 v122, 0x358637bd
	v_fmamk_f32 v121, v121, 0x3a800000, v122
	v_rsq_f32_e32 v121, v121
	s_nop 0
	v_mul_f32_e32 v88, v88, v121
	v_mul_f32_e32 v89, v89, v121
	v_mul_f32_e32 v90, v90, v121
	v_mul_f32_e32 v91, v91, v121
	v_mul_f32_e32 v92, v92, v121
	v_mul_f32_e32 v93, v93, v121
	v_mul_f32_e32 v94, v94, v121
	v_mul_f32_e32 v95, v95, v121
	v_mul_f32_e32 v96, v96, v121
	v_mul_f32_e32 v97, v97, v121
	v_mul_f32_e32 v98, v98, v121
	v_mul_f32_e32 v99, v99, v121
	v_mul_f32_e32 v100, v100, v121
	v_mul_f32_e32 v101, v101, v121
	v_mul_f32_e32 v102, v102, v121
	v_mul_f32_e32 v103, v103, v121
	v_mul_f32_e32 v88, v68, v88
	v_mul_f32_e32 v89, v69, v89
	v_mul_f32_e32 v90, v70, v90
	v_mul_f32_e32 v91, v71, v91
	v_mul_f32_e32 v92, v72, v92
	v_mul_f32_e32 v93, v73, v93
	v_mul_f32_e32 v94, v74, v94
	v_mul_f32_e32 v95, v75, v95
	v_mul_f32_e32 v96, v76, v96
	v_mul_f32_e32 v97, v77, v97
	v_mul_f32_e32 v98, v78, v98
	v_mul_f32_e32 v99, v79, v99
	v_mul_f32_e32 v100, v80, v100
	v_mul_f32_e32 v101, v81, v101
	v_mul_f32_e32 v102, v82, v102
	v_mul_f32_e32 v103, v83, v103
	v_cvt_pk_bf16_f32 v124, v88, v89
	v_cvt_pk_bf16_f32 v125, v90, v91
	v_cvt_pk_bf16_f32 v126, v92, v93
	v_cvt_pk_bf16_f32 v127, v94, v95
	v_cvt_pk_bf16_f32 v128, v96, v97
	v_cvt_pk_bf16_f32 v129, v98, v99
	v_cvt_pk_bf16_f32 v130, v100, v101
	v_cvt_pk_bf16_f32 v131, v102, v103
	global_store_dwordx2 v86, v[124:125], s[50:51]
	global_store_dwordx2 v86, v[126:127], s[50:51] offset:512
	global_store_dwordx2 v86, v[128:129], s[50:51] offset:1024
	global_store_dwordx2 v86, v[130:131], s[50:51] offset:1536
	s_mov_b32 s74, s80
	s_branch .Lrms_done
.Lrms_last1:
	s_waitcnt vmcnt(0)
	v_mul_f32_e32 v120, v104, v104
	v_fmac_f32_e32 v120, v105, v105
	v_fmac_f32_e32 v120, v106, v106
	v_fmac_f32_e32 v120, v107, v107
	v_fmac_f32_e32 v120, v108, v108
	v_fmac_f32_e32 v120, v109, v109
	v_fmac_f32_e32 v120, v110, v110
	v_fmac_f32_e32 v120, v111, v111
	v_fmac_f32_e32 v120, v112, v112
	v_fmac_f32_e32 v120, v113, v113
	v_fmac_f32_e32 v120, v114, v114
	v_fmac_f32_e32 v120, v115, v115
	v_fmac_f32_e32 v120, v116, v116
	v_fmac_f32_e32 v120, v117, v117
	v_fmac_f32_e32 v120, v118, v118
	v_fmac_f32_e32 v120, v119, v119
	s_nop 1
	v_add_f32_dpp v120, v120, v120 quad_perm:[1,0,3,2] row_mask:0xf bank_mask:0xf
	s_nop 1
	v_add_f32_dpp v120, v120, v120 quad_perm:[2,3,0,1] row_mask:0xf bank_mask:0xf
	s_nop 1
	v_add_f32_dpp v120, v120, v120 row_half_mirror row_mask:0xf bank_mask:0xf
	s_nop 1
	v_add_f32_dpp v120, v120, v120 row_mirror row_mask:0xf bank_mask:0xf
	s_nop 1
	v_readlane_b32 s87, v120, 0
	v_readlane_b32 s88, v120, 16
	v_readlane_b32 s89, v120, 32
	v_readlane_b32 s90, v120, 48
	s_nop 1
	v_mov_b32_e32 v121, s87
	v_add_f32_e32 v121, s88, v121
	v_add_f32_e32 v121, s89, v121
	v_add_f32_e32 v121, s90, v121
	v_mov_b32_e32 v122, 0x358637bd
	v_fmamk_f32 v121, v121, 0x3a800000, v122
	v_rsq_f32_e32 v121, v121
	s_nop 0
	v_mul_f32_e32 v104, v104, v121
	v_mul_f32_e32 v105, v105, v121
	v_mul_f32_e32 v106, v106, v121
	v_mul_f32_e32 v107, v107, v121
	v_mul_f32_e32 v108, v108, v121
	v_mul_f32_e32 v109, v109, v121
	v_mul_f32_e32 v110, v110, v121
	v_mul_f32_e32 v111, v111, v121
	v_mul_f32_e32 v112, v112, v121
	v_mul_f32_e32 v113, v113, v121
	v_mul_f32_e32 v114, v114, v121
	v_mul_f32_e32 v115, v115, v121
	v_mul_f32_e32 v116, v116, v121
	v_mul_f32_e32 v117, v117, v121
	v_mul_f32_e32 v118, v118, v121
	v_mul_f32_e32 v119, v119, v121
	v_mul_f32_e32 v104, v68, v104
	v_mul_f32_e32 v105, v69, v105
	v_mul_f32_e32 v106, v70, v106
	v_mul_f32_e32 v107, v71, v107
	v_mul_f32_e32 v108, v72, v108
	v_mul_f32_e32 v109, v73, v109
	v_mul_f32_e32 v110, v74, v110
	v_mul_f32_e32 v111, v75, v111
	v_mul_f32_e32 v112, v76, v112
	v_mul_f32_e32 v113, v77, v113
	v_mul_f32_e32 v114, v78, v114
	v_mul_f32_e32 v115, v79, v115
	v_mul_f32_e32 v116, v80, v116
	v_mul_f32_e32 v117, v81, v117
	v_mul_f32_e32 v118, v82, v118
	v_mul_f32_e32 v119, v83, v119
	v_cvt_pk_bf16_f32 v124, v104, v105
	v_cvt_pk_bf16_f32 v125, v106, v107
	v_cvt_pk_bf16_f32 v126, v108, v109
	v_cvt_pk_bf16_f32 v127, v110, v111
	v_cvt_pk_bf16_f32 v128, v112, v113
	v_cvt_pk_bf16_f32 v129, v114, v115
	v_cvt_pk_bf16_f32 v130, v116, v117
	v_cvt_pk_bf16_f32 v131, v118, v119
	global_store_dwordx2 v87, v[124:125], s[50:51]
	global_store_dwordx2 v87, v[126:127], s[50:51] offset:512
	global_store_dwordx2 v87, v[128:129], s[50:51] offset:1024
	global_store_dwordx2 v87, v[130:131], s[50:51] offset:1536
	s_mov_b32 s74, s80
.Lrms_done:
	s_cmpk_lt_i32 s74, 0x2560
	s_cbranch_scc0 .LBB0_44
	s_branch .LBB0_18
